# cross-attn tile loop: replaced full lgkmcnt(0) drains with counted lgkmcnt ladders (same pattern the compiler emits in the peeled last tile)
# speedup vs baseline: 1.0285x; 1.0017x over previous
; #define LAS __attribute__((address_space(3)))
; template <int D, int DV, int MODE, int NMAP, int KT> ...
;     ...
;         if (MODE == 0 || kt * KT <= rowmin + 15) {
;             const LAS bf16_t* Ks = (const LAS bf16_t*)(lds + cur); const LAS bf16_t* Vt = (const LAS bf16_t*)(lds + cur + KS_BYTES);
;             const bool diag = (MODE != 0) && (kt * KT + KT - 1 > rowmin);
;             bf16x8 pb[NMAP][KK2];
;             f32x4 sall[NMAP][NB];
; #pragma unroll
;             for (int mp = 0; mp < NMAP; ++mp) {
;                 f32x4 (&s)[NB] = sall[mp];
;                 constexpr int KD = D / 32, NBB = (KD >= 8) ? 1 : (8 / KD), NSB = NB / NBB;
;                 bf16x8 kfr[2][NBB][KD];
;     ...
;                 AT_SLOAD(0, 0);
; #pragma unroll
;                 for (int bi = 0; bi < NSB; ++bi) {
;                     if (bi + 1 < NSB) AT_SLOAD(bi + 1, (bi + 1) & 1);
;                     __builtin_amdgcn_sched_barrier(0);
;                     __builtin_amdgcn_s_setprio(1);
; #pragma unroll
;                     for (int x_ = 0; x_ < NBB; ++x_) { const int nb = bi * NBB + x_;
;                         s[nb] = __builtin_amdgcn_mfma_f32_16x16x32_bf16(kfr[bi & 1][x_][0], qf[mp][0], (f32x4){0.f, 0.f, 0.f, 0.f}, 0, 0, 0);
; #pragma unroll
;                         for (int kk = 1; kk < KD; ++kk) s[nb] = __builtin_amdgcn_mfma_f32_16x16x32_bf16(kfr[bi & 1][x_][kk], qf[mp][kk], s[nb], 0, 0, 0); }
;                     __builtin_amdgcn_s_setprio(0);
;                     __builtin_amdgcn_sched_barrier(0);
;                 }
;     ...
;             }
; #pragma unroll
;             for (int mp = 0; mp < NMAP; ++mp) {
;                 f32x4 (&s)[NB] = sall[mp];
;                 if (MODE < 2) {
;                     if (diag) {
; #pragma unroll
;                         for (int nb = 0; nb < NB; ++nb)
; #pragma unroll
;                             for (int j = 0; j < 4; ++j) { if (kt * KT + nb * 16 + g4 * 4 + j > myrow) s[nb][j] = -INFINITY; }
;                     }
;                     float mx = fmaxf(fmaxf(s[0][0], s[0][1]), s[0][2]);
;                     mx = fmaxf(fmaxf(mx, s[0][3]), s[1][0]); mx = fmaxf(fmaxf(mx, s[1][1]), s[1][2]); mx = fmaxf(fmaxf(mx, s[1][3]), s[2][0]);
;                     mx = fmaxf(fmaxf(mx, s[2][1]), s[2][2]); mx = fmaxf(fmaxf(mx, s[2][3]), s[3][0]); mx = fmaxf(fmaxf(mx, s[3][1]), s[3][2]); mx = fmaxf(mx, s[3][3]);
; #pragma unroll
.LBB0_603:
	s_bitcmp1_b32 s15, 0
	s_cselect_b32 s15, 0x11400, 0
	s_add_i32 s15, s15, 0
	v_add3_u32 v184, s15, v148, v170
	ds_read_b128 v[130:133], v184
	ds_read_b128 v[134:137], v184 offset:64
	ds_read_b128 v[138:141], v184 offset:128
	ds_read_b128 v[142:145], v184 offset:192
	ds_read_b128 v[176:179], v184 offset:256
	ds_read_b128 v[180:183], v184 offset:320
	ds_read_b128 v[194:197], v184 offset:384
	ds_read_b128 v[198:201], v184 offset:448
	ds_read_b128 v[202:205], v184 offset:8448
	ds_read_b128 v[206:209], v184 offset:8512
	ds_read_b128 v[226:229], v184 offset:8576
	ds_read_b128 v[230:233], v184 offset:8640
	ds_read_b128 v[234:237], v184 offset:8704
	ds_read_b128 v[238:241], v184 offset:8768
	ds_read_b128 v[242:245], v184 offset:8832
	ds_read_b128 v[246:249], v184 offset:8896
	s_setprio 1
	s_waitcnt lgkmcnt(14)
	v_mfma_f32_16x16x32_bf16 v[130:133], v[130:133], v[66:69], 0
	v_mfma_f32_16x16x32_bf16 v[130:133], v[134:137], v[70:73], v[130:133]
	s_waitcnt lgkmcnt(13)
	v_mfma_f32_16x16x32_bf16 v[130:133], v[138:141], v[74:77], v[130:133]
	s_waitcnt lgkmcnt(12)
	v_mfma_f32_16x16x32_bf16 v[130:133], v[142:145], v[78:81], v[130:133]
	s_waitcnt lgkmcnt(11)
	v_mfma_f32_16x16x32_bf16 v[130:133], v[176:179], v[82:85], v[130:133]
	s_waitcnt lgkmcnt(10)
	v_mfma_f32_16x16x32_bf16 v[130:133], v[180:183], v[86:89], v[130:133]
	s_waitcnt lgkmcnt(9)
	v_mfma_f32_16x16x32_bf16 v[130:133], v[194:197], v[90:93], v[130:133]
	s_waitcnt lgkmcnt(8)
	v_mfma_f32_16x16x32_bf16 v[142:145], v[198:201], v[94:97], v[130:133]
	s_setprio 0
	s_nop 5
	ds_read_b128 v[130:133], v184 offset:16896
	ds_read_b128 v[134:137], v184 offset:16960
	ds_read_b128 v[176:179], v184 offset:17024
	ds_read_b128 v[180:183], v184 offset:17088
	ds_read_b128 v[194:197], v184 offset:17152
	ds_read_b128 v[198:201], v184 offset:17216
	ds_read_b128 v[250:253], v184 offset:17280
	ds_read_b128 v[212:215], v184 offset:17344
	s_setprio 1
	s_waitcnt lgkmcnt(14)
	v_mfma_f32_16x16x32_bf16 v[138:141], v[202:205], v[66:69], 0
	v_mfma_f32_16x16x32_bf16 v[138:141], v[206:209], v[70:73], v[138:141]
	s_waitcnt lgkmcnt(13)
	v_mfma_f32_16x16x32_bf16 v[138:141], v[226:229], v[74:77], v[138:141]
	s_waitcnt lgkmcnt(12)
	v_mfma_f32_16x16x32_bf16 v[138:141], v[230:233], v[78:81], v[138:141]
	s_waitcnt lgkmcnt(11)
	v_mfma_f32_16x16x32_bf16 v[138:141], v[234:237], v[82:85], v[138:141]
	s_waitcnt lgkmcnt(10)
	v_mfma_f32_16x16x32_bf16 v[138:141], v[238:241], v[86:89], v[138:141]
	s_waitcnt lgkmcnt(9)
	v_mfma_f32_16x16x32_bf16 v[138:141], v[242:245], v[90:93], v[138:141]
	s_waitcnt lgkmcnt(8)
	v_mfma_f32_16x16x32_bf16 v[138:141], v[246:249], v[94:97], v[138:141]
	s_setprio 0
	ds_read_b128 v[202:205], v184 offset:25344
	ds_read_b128 v[206:209], v184 offset:25408
	ds_read_b128 v[226:229], v184 offset:25472
	ds_read_b128 v[230:233], v184 offset:25536
	ds_read_b128 v[234:237], v184 offset:25600
	ds_read_b128 v[238:241], v184 offset:25664
	ds_read_b128 v[242:245], v184 offset:25728
	ds_read_b128 v[246:249], v184 offset:25792
	s_setprio 1
	s_waitcnt lgkmcnt(14)
	v_mfma_f32_16x16x32_bf16 v[130:133], v[130:133], v[66:69], 0
	v_mfma_f32_16x16x32_bf16 v[130:133], v[134:137], v[70:73], v[130:133]
	s_waitcnt lgkmcnt(13)
	v_mfma_f32_16x16x32_bf16 v[130:133], v[176:179], v[74:77], v[130:133]
	s_waitcnt lgkmcnt(12)
	v_mfma_f32_16x16x32_bf16 v[130:133], v[180:183], v[78:81], v[130:133]
	s_waitcnt lgkmcnt(11)
	v_mfma_f32_16x16x32_bf16 v[130:133], v[194:197], v[82:85], v[130:133]
	s_waitcnt lgkmcnt(10)
	v_mfma_f32_16x16x32_bf16 v[130:133], v[198:201], v[86:89], v[130:133]
	s_waitcnt lgkmcnt(9)
	v_mfma_f32_16x16x32_bf16 v[130:133], v[250:253], v[90:93], v[130:133]
	s_waitcnt lgkmcnt(8)
	v_mfma_f32_16x16x32_bf16 v[134:137], v[212:215], v[94:97], v[130:133]
	s_setprio 0
	s_setprio 1
	s_waitcnt lgkmcnt(7)
	v_mfma_f32_16x16x32_bf16 v[130:133], v[202:205], v[66:69], 0
	s_waitcnt lgkmcnt(6)
	v_mfma_f32_16x16x32_bf16 v[130:133], v[206:209], v[70:73], v[130:133]
	s_waitcnt lgkmcnt(5)
	v_mfma_f32_16x16x32_bf16 v[130:133], v[226:229], v[74:77], v[130:133]
	s_waitcnt lgkmcnt(4)
	v_mfma_f32_16x16x32_bf16 v[130:133], v[230:233], v[78:81], v[130:133]
	s_waitcnt lgkmcnt(3)
	v_mfma_f32_16x16x32_bf16 v[130:133], v[234:237], v[82:85], v[130:133]
	s_waitcnt lgkmcnt(2)
	v_mfma_f32_16x16x32_bf16 v[130:133], v[238:241], v[86:89], v[130:133]
	s_waitcnt lgkmcnt(1)
	v_mfma_f32_16x16x32_bf16 v[130:133], v[242:245], v[90:93], v[130:133]
	s_waitcnt lgkmcnt(0)
	v_mfma_f32_16x16x32_bf16 v[130:133], v[246:249], v[94:97], v[130:133]
	s_setprio 0
	v_max_f32_e32 v176, v143, v143
	v_max_f32_e32 v177, v142, v142
	v_max_f32_e32 v176, v177, v176
	v_max3_f32 v176, v176, v144, v145
	v_max3_f32 v176, v176, v138, v139
	v_max3_f32 v176, v176, v140, v141
	v_max3_f32 v176, v176, v134, v135
	v_max3_f32 v176, v176, v136, v137
	v_max3_f32 v176, v176, v130, v131
	v_max3_f32 v176, v176, v132, v133
	v_mov_b32_e32 v177, v176
	s_nop 1
	v_permlane16_swap_b32_e32 v176, v177
	v_max_f32_e32 v177, v177, v177
	v_max_f32_e32 v176, v176, v176
	v_max_f32_e32 v176, v176, v177
	v_mov_b32_e32 v177, v176
	s_nop 1
	v_permlane32_swap_b32_e32 v176, v177
	v_max_f32_e32 v177, v177, v177
	v_max_f32_e32 v176, v176, v176
	v_max_f32_e32 v176, v176, v177
	v_mul_f32_e32 v176, 0x3db8aa3b, v176
	v_add_f32_e32 v177, 0x40c00000, v175
	v_cmp_gt_f32_e32 vcc, v176, v177
	s_cbranch_vccz .LBB0_605
; template <int D, int DV, int MODE, int NMAP, int KT> ...
;     ...
;                     if (__any(mx > m[mp] + 6.0f)) {
;                         const float mn = fmaxf(m[mp], mx); const float al = __builtin_amdgcn_exp2f(m[mp] - mn); m[mp] = mn; l[mp] *= al;
; #pragma unroll
;                         for (int cb = 0; cb < DV / 16; ++cb) o[mp][cb] = o[mp][cb] * al;
;                     }
;                     const float nm = -m[mp]; float ps = 0.f;
; #pragma unroll
;                     for (int nb = 0; nb < NB; ++nb)
; #pragma unroll
;                         for (int j = 0; j < 4; ++j) { const float p = __builtin_amdgcn_exp2f(fmaf(s[nb][j], sc, nm)); ps += p; s[nb][j] = p; }
;                     l[mp] += ps;
;                 } else {
;                     const float rowf = __builtin_amdgcn_exp2f(l2g * (float)(myrow - kt * KT));
; #pragma unroll
;                     for (int nb = 0; nb < NB; ++nb)
; #pragma unroll
;                         for (int j = 0; j < 4; ++j) { float p = s[nb][j] * (rowf * ck[nb][j]); if (diag && (kt * KT + nb * 16 + g4 * 4 + j > myrow)) p = 0.f; s[nb][j] = p; }
;                 }
; #pragma unroll
;                 for (int kk = 0; kk < KK2; ++kk) { u32x4 wv; wv.x = cvt_pk_bf16(s[2 * kk][0], s[2 * kk][1]); wv.y = cvt_pk_bf16(s[2 * kk][2], s[2 * kk][3]);
;                     wv.z = cvt_pk_bf16(s[2 * kk + 1][0], s[2 * kk + 1][1]); wv.w = cvt_pk_bf16(s[2 * kk + 1][2], s[2 * kk + 1][3]); pb[mp][kk] = __builtin_bit_cast(bf16x8, wv); }
;             }
;             {
;                 constexpr int CBB = 4, NCB = (DV / 16) / CBB, NVB = KK2 * NCB;
;                 bf16x8 vfr[2][CBB];
;     ...
;                 AT_VLOAD(0, 0);
; #pragma unroll
;                 for (int b_ = 0; b_ < NVB; ++b_) {
;                     if (b_ + 1 < NVB) AT_VLOAD(b_ + 1, (b_ + 1) & 1);
;                     __builtin_amdgcn_sched_barrier(0);
;                     const int kk_ = b_ / NCB, c0_ = (b_ % NCB) * CBB;
;                     __builtin_amdgcn_s_setprio(1);
; #pragma unroll
;                     for (int x_ = 0; x_ < CBB; ++x_)
; #pragma unroll
;                         for (int mp = 0; mp < NMAP; ++mp) o[mp][c0_ + x_] = __builtin_amdgcn_mfma_f32_16x16x32_bf16(vfr[b_ & 1][x_], pb[mp][kk_], o[mp][c0_ + x_], 0, 0, 0);
;                     __builtin_amdgcn_s_setprio(0);
;                     __builtin_amdgcn_sched_barrier(0);
;                 }
	v_max_f32_e32 v176, v176, v176
	v_max_f32_e32 v177, v175, v175
	v_max_f32_e32 v177, v177, v176
	v_sub_f32_e32 v175, v175, v177
	v_exp_f32_e32 v176, v175
	v_mov_b32_e32 v175, v177
	v_mul_f32_e32 v159, v159, v176
	v_pk_mul_f32 v[64:65], v[64:65], v[176:177] op_sel_hi:[1,0]
	v_pk_mul_f32 v[62:63], v[62:63], v[176:177] op_sel_hi:[1,0]
	v_pk_mul_f32 v[60:61], v[60:61], v[176:177] op_sel_hi:[1,0]
	v_pk_mul_f32 v[58:59], v[58:59], v[176:177] op_sel_hi:[1,0]
	v_pk_mul_f32 v[56:57], v[56:57], v[176:177] op_sel_hi:[1,0]
	v_pk_mul_f32 v[54:55], v[54:55], v[176:177] op_sel_hi:[1,0]
	v_pk_mul_f32 v[52:53], v[52:53], v[176:177] op_sel_hi:[1,0]
	v_pk_mul_f32 v[50:51], v[50:51], v[176:177] op_sel_hi:[1,0]
	v_pk_mul_f32 v[48:49], v[48:49], v[176:177] op_sel_hi:[1,0]
	v_pk_mul_f32 v[46:47], v[46:47], v[176:177] op_sel_hi:[1,0]
	v_pk_mul_f32 v[44:45], v[44:45], v[176:177] op_sel_hi:[1,0]
	v_pk_mul_f32 v[42:43], v[42:43], v[176:177] op_sel_hi:[1,0]
	v_pk_mul_f32 v[40:41], v[40:41], v[176:177] op_sel_hi:[1,0]
	v_pk_mul_f32 v[38:39], v[38:39], v[176:177] op_sel_hi:[1,0]
	v_pk_mul_f32 v[36:37], v[36:37], v[176:177] op_sel_hi:[1,0]
	v_pk_mul_f32 v[34:35], v[34:35], v[176:177] op_sel_hi:[1,0]
	v_pk_mul_f32 v[32:33], v[32:33], v[176:177] op_sel_hi:[1,0]
	v_pk_mul_f32 v[30:31], v[30:31], v[176:177] op_sel_hi:[1,0]
	v_pk_mul_f32 v[28:29], v[28:29], v[176:177] op_sel_hi:[1,0]
	v_pk_mul_f32 v[26:27], v[26:27], v[176:177] op_sel_hi:[1,0]
	v_pk_mul_f32 v[24:25], v[24:25], v[176:177] op_sel_hi:[1,0]
	v_pk_mul_f32 v[22:23], v[22:23], v[176:177] op_sel_hi:[1,0]
	v_pk_mul_f32 v[20:21], v[20:21], v[176:177] op_sel_hi:[1,0]
	v_pk_mul_f32 v[18:19], v[18:19], v[176:177] op_sel_hi:[1,0]
	v_pk_mul_f32 v[16:17], v[16:17], v[176:177] op_sel_hi:[1,0]
	v_pk_mul_f32 v[14:15], v[14:15], v[176:177] op_sel_hi:[1,0]
	v_pk_mul_f32 v[12:13], v[12:13], v[176:177] op_sel_hi:[1,0]
	v_pk_mul_f32 v[10:11], v[10:11], v[176:177] op_sel_hi:[1,0]
	v_pk_mul_f32 v[8:9], v[8:9], v[176:177] op_sel_hi:[1,0]
	v_pk_mul_f32 v[6:7], v[6:7], v[176:177] op_sel_hi:[1,0]
	v_pk_mul_f32 v[4:5], v[4:5], v[176:177] op_sel_hi:[1,0]
	v_pk_mul_f32 v[2:3], v[2:3], v[176:177] op_sel_hi:[1,0]
.LBB0_605:
	v_fma_f32 v142, v142, s0, -v175
	v_exp_f32_e32 v142, v142
	v_fma_f32 v143, v143, s0, -v175
	v_exp_f32_e32 v143, v143
	v_fma_f32 v144, v144, s0, -v175
	v_exp_f32_e32 v144, v144
	v_fma_f32 v145, v145, s0, -v175
	v_exp_f32_e32 v145, v145
	v_fma_f32 v138, v138, s0, -v175
	v_add_f32_e32 v176, 0, v142
	v_exp_f32_e32 v138, v138
	v_fma_f32 v139, v139, s0, -v175
	v_add_f32_e32 v176, v143, v176
	v_exp_f32_e32 v139, v139
	v_fma_f32 v140, v140, s0, -v175
	v_add_f32_e32 v176, v144, v176
	v_exp_f32_e32 v140, v140
	v_fma_f32 v141, v141, s0, -v175
	v_add_f32_e32 v176, v145, v176
	v_exp_f32_e32 v141, v141
	v_fma_f32 v134, v134, s0, -v175
	v_add_f32_e32 v176, v138, v176
	v_exp_f32_e32 v177, v134
	v_add_f32_e32 v176, v139, v176
	v_add_f32_e32 v176, v140, v176
	v_add_f32_e32 v176, v141, v176
	v_fma_f32 v135, v135, s0, -v175
	v_add_f32_e32 v134, v177, v176
	v_exp_f32_e32 v176, v135
	v_fma_f32 v135, v136, s0, -v175
	v_exp_f32_e32 v178, v135
	v_fma_f32 v135, v137, s0, -v175
	v_exp_f32_e32 v179, v135
	v_fma_f32 v130, v130, s0, -v175
	v_exp_f32_e32 v180, v130
	v_fma_f32 v131, v131, s0, -v175
	v_add_f32_e32 v134, v176, v134
	v_exp_f32_e32 v181, v131
	v_fma_f32 v131, v132, s0, -v175
	v_add_f32_e32 v134, v178, v134
	v_exp_f32_e32 v182, v131
	v_fma_f32 v131, v133, s0, -v175
	v_add_f32_e32 v134, v179, v134
	v_exp_f32_e32 v133, v131
	v_add_f32_e32 v130, v180, v134
	v_add_f32_e32 v130, v181, v130
	v_add_f32_e32 v130, v182, v130
	v_add3_u32 v184, s15, v158, v149
	v_add_f32_e32 v130, v133, v130
	v_add_u32_e32 v210, 0x8000, v184
	v_add_u32_e32 v212, 0x8800, v184
	v_add_u32_e32 v213, 0x9000, v184
	v_add_u32_e32 v214, 0x9800, v184
	v_add_u32_e32 v215, 0xa800, v184
	v_add_u32_e32 v216, 0xb000, v184
	v_add_u32_e32 v217, 0xb800, v184
	v_add_u32_e32 v226, 0xc000, v184
	v_add_f32_e32 v159, v159, v130
	v_cvt_pk_bf16_f32 v134, v142, v143
	v_cvt_pk_bf16_f32 v135, v144, v145
	v_cvt_pk_bf16_f32 v136, v138, v139
	v_cvt_pk_bf16_f32 v137, v140, v141
	v_cvt_pk_bf16_f32 v130, v177, v176
	v_cvt_pk_bf16_f32 v131, v178, v179
	v_cvt_pk_bf16_f32 v132, v180, v181
	v_cvt_pk_bf16_f32 v133, v182, v133
	ds_read_b64 v[138:139], v210 offset:1024
	ds_read_b64 v[140:141], v210 offset:1056
	ds_read_b64 v[142:143], v212 offset:1280
	ds_read_b64 v[144:145], v212 offset:1312
	ds_read_b64 v[176:177], v213 offset:1536
	ds_read_b64 v[178:179], v213 offset:1568
	ds_read_b64 v[180:181], v214 offset:1792
	ds_read_b64 v[182:183], v214 offset:1824
	ds_read_b64 v[194:195], v215
	ds_read_b64 v[196:197], v215 offset:32
	ds_read_b64 v[198:199], v216 offset:256
	ds_read_b64 v[200:201], v216 offset:288
	ds_read_b64 v[202:203], v217 offset:512
	ds_read_b64 v[204:205], v217 offset:544
	ds_read_b64 v[206:207], v226 offset:768
	ds_read_b64 v[208:209], v226 offset:800
	v_add_u32_e32 v185, 0x8400, v184
	s_setprio 1
	s_waitcnt lgkmcnt(14)
	v_mfma_f32_16x16x32_bf16 v[62:65], v[138:141], v[134:137], v[62:65]
	s_waitcnt lgkmcnt(12)
	v_mfma_f32_16x16x32_bf16 v[58:61], v[142:145], v[134:137], v[58:61]
	s_waitcnt lgkmcnt(10)
	v_mfma_f32_16x16x32_bf16 v[54:57], v[176:179], v[134:137], v[54:57]
	s_waitcnt lgkmcnt(8)
; template <int D, int DV, int MODE, int NMAP, int KT> ...
;     ...
;                 constexpr int CBB = 4, NCB = (DV / 16) / CBB, NVB = KK2 * NCB;
;                 bf16x8 vfr[2][CBB];
;     ...
;                 AT_VLOAD(0, 0);
; #pragma unroll
;                 for (int b_ = 0; b_ < NVB; ++b_) {
;                     if (b_ + 1 < NVB) AT_VLOAD(b_ + 1, (b_ + 1) & 1);
;                     __builtin_amdgcn_sched_barrier(0);
;                     const int kk_ = b_ / NCB, c0_ = (b_ % NCB) * CBB;
;                     __builtin_amdgcn_s_setprio(1);
; #pragma unroll
;                     for (int x_ = 0; x_ < CBB; ++x_)
; #pragma unroll
;                         for (int mp = 0; mp < NMAP; ++mp) o[mp][c0_ + x_] = __builtin_amdgcn_mfma_f32_16x16x32_bf16(vfr[b_ & 1][x_], pb[mp][kk_], o[mp][c0_ + x_], 0, 0, 0);
;                     __builtin_amdgcn_s_setprio(0);
;                     __builtin_amdgcn_sched_barrier(0);
;                 }
	v_mfma_f32_16x16x32_bf16 v[50:53], v[180:183], v[134:137], v[50:53]
	s_setprio 0
	v_add_u32_e32 v227, 0xc800, v184
	v_add_u32_e32 v228, 0xd000, v184
	v_add_u32_e32 v229, 0xd800, v184
	v_add_u32_e32 v230, 0xe000, v184
	ds_read_b64 v[138:139], v227 offset:1024
	ds_read_b64 v[140:141], v227 offset:1056
	ds_read_b64 v[142:143], v228 offset:1280
	ds_read_b64 v[144:145], v228 offset:1312
	ds_read_b64 v[176:177], v229 offset:1536
	ds_read_b64 v[178:179], v229 offset:1568
	ds_read_b64 v[180:181], v230 offset:1792
	ds_read_b64 v[182:183], v230 offset:1824
	s_setprio 1
	s_waitcnt lgkmcnt(14)
	v_mfma_f32_16x16x32_bf16 v[46:49], v[194:197], v[134:137], v[46:49]
	s_waitcnt lgkmcnt(12)
	v_mfma_f32_16x16x32_bf16 v[42:45], v[198:201], v[134:137], v[42:45]
	s_waitcnt lgkmcnt(10)
	v_mfma_f32_16x16x32_bf16 v[38:41], v[202:205], v[134:137], v[38:41]
	s_waitcnt lgkmcnt(8)
	v_mfma_f32_16x16x32_bf16 v[34:37], v[206:209], v[134:137], v[34:37]
	s_setprio 0
	v_add_u32_e32 v231, 0xf000, v184
	v_add_u32_e32 v232, 0xf800, v184
	v_add_u32_e32 v202, 0x7800, v185
	v_add_u32_e32 v185, 0x8000, v185
	ds_read_b64 v[194:195], v231
	ds_read_b64 v[196:197], v231 offset:32
	ds_read_b64 v[198:199], v232 offset:256
	ds_read_b64 v[200:201], v232 offset:288
	ds_read_b64 v[204:205], v202 offset:1568
	ds_read_b64 v[202:203], v202 offset:1536
	ds_read_b64 v[206:207], v185 offset:1792
	ds_read_b64 v[208:209], v185 offset:1824
	s_setprio 1
	s_waitcnt lgkmcnt(14)
	v_mfma_f32_16x16x32_bf16 v[30:33], v[138:141], v[134:137], v[30:33]
	s_waitcnt lgkmcnt(12)
	v_mfma_f32_16x16x32_bf16 v[26:29], v[142:145], v[134:137], v[26:29]
	s_waitcnt lgkmcnt(10)
	v_mfma_f32_16x16x32_bf16 v[22:25], v[176:179], v[134:137], v[22:25]
	s_waitcnt lgkmcnt(8)
	v_mfma_f32_16x16x32_bf16 v[18:21], v[180:183], v[134:137], v[18:21]
	s_setprio 0
	ds_read_b64 v[138:139], v210 offset:1088
	ds_read_b64 v[140:141], v210 offset:1120
	ds_read_b64 v[142:143], v212 offset:1344
	ds_read_b64 v[144:145], v212 offset:1376
	ds_read_b64 v[176:177], v213 offset:1600
	ds_read_b64 v[178:179], v213 offset:1632
	ds_read_b64 v[180:181], v214 offset:1856
	ds_read_b64 v[182:183], v214 offset:1888
	v_add_u32_e32 v184, 0x8440, v184
	s_setprio 1
	s_waitcnt lgkmcnt(14)
	v_mfma_f32_16x16x32_bf16 v[14:17], v[194:197], v[134:137], v[14:17]
	s_waitcnt lgkmcnt(12)
	v_mfma_f32_16x16x32_bf16 v[10:13], v[198:201], v[134:137], v[10:13]
	s_waitcnt lgkmcnt(10)
	v_mfma_f32_16x16x32_bf16 v[6:9], v[202:205], v[134:137], v[6:9]
	s_waitcnt lgkmcnt(8)
	v_mfma_f32_16x16x32_bf16 v[2:5], v[206:209], v[134:137], v[2:5]
	s_setprio 0
	ds_read_b64 v[134:135], v215 offset:64
	ds_read_b64 v[136:137], v215 offset:96
	ds_read_b64 v[194:195], v216 offset:320
	ds_read_b64 v[196:197], v216 offset:352
	ds_read_b64 v[198:199], v217 offset:576
	ds_read_b64 v[200:201], v217 offset:608
	ds_read_b64 v[202:203], v226 offset:832
	ds_read_b64 v[204:205], v226 offset:864
	s_setprio 1
	s_waitcnt lgkmcnt(14)
	v_mfma_f32_16x16x32_bf16 v[62:65], v[138:141], v[130:133], v[62:65]
	s_waitcnt lgkmcnt(12)
	v_mfma_f32_16x16x32_bf16 v[58:61], v[142:145], v[130:133], v[58:61]
	s_waitcnt lgkmcnt(10)
	v_mfma_f32_16x16x32_bf16 v[54:57], v[176:179], v[130:133], v[54:57]
	s_waitcnt lgkmcnt(8)
	v_mfma_f32_16x16x32_bf16 v[50:53], v[180:183], v[130:133], v[50:53]
	s_setprio 0
	ds_read_b64 v[138:139], v227 offset:1088
	ds_read_b64 v[140:141], v227 offset:1120
	ds_read_b64 v[142:143], v228 offset:1344
	ds_read_b64 v[144:145], v228 offset:1376
	ds_read_b64 v[176:177], v229 offset:1600
	ds_read_b64 v[178:179], v229 offset:1632
	ds_read_b64 v[180:181], v230 offset:1856
	ds_read_b64 v[182:183], v230 offset:1888
	s_setprio 1
	s_waitcnt lgkmcnt(14)
	v_mfma_f32_16x16x32_bf16 v[46:49], v[134:137], v[130:133], v[46:49]
	s_waitcnt lgkmcnt(12)
	v_mfma_f32_16x16x32_bf16 v[42:45], v[194:197], v[130:133], v[42:45]
	s_waitcnt lgkmcnt(10)
	v_mfma_f32_16x16x32_bf16 v[38:41], v[198:201], v[130:133], v[38:41]
	s_waitcnt lgkmcnt(8)
	v_mfma_f32_16x16x32_bf16 v[34:37], v[202:205], v[130:133], v[34:37]
	s_setprio 0
	ds_read_b64 v[134:135], v231 offset:64
	ds_read_b64 v[136:137], v231 offset:96
	ds_read_b64 v[194:195], v232 offset:320
	ds_read_b64 v[196:197], v232 offset:352
	v_add_u32_e32 v185, 0x7800, v184
	v_add_u32_e32 v184, 0x8000, v184
	ds_read_b64 v[198:199], v185 offset:1536
	ds_read_b64 v[200:201], v185 offset:1568
	ds_read_b64 v[202:203], v184 offset:1792
	ds_read_b64 v[204:205], v184 offset:1824
	s_setprio 1
	s_waitcnt lgkmcnt(14)
	v_mfma_f32_16x16x32_bf16 v[30:33], v[138:141], v[130:133], v[30:33]
	s_waitcnt lgkmcnt(12)
	v_mfma_f32_16x16x32_bf16 v[26:29], v[142:145], v[130:133], v[26:29]
	s_waitcnt lgkmcnt(10)
	v_mfma_f32_16x16x32_bf16 v[22:25], v[176:179], v[130:133], v[22:25]
	s_waitcnt lgkmcnt(8)
	v_mfma_f32_16x16x32_bf16 v[18:21], v[180:183], v[130:133], v[18:21]
	s_setprio 0
	s_setprio 1
	s_waitcnt lgkmcnt(6)
	v_mfma_f32_16x16x32_bf16 v[14:17], v[134:137], v[130:133], v[14:17]
	s_waitcnt lgkmcnt(4)
	v_mfma_f32_16x16x32_bf16 v[10:13], v[194:197], v[130:133], v[10:13]
	s_waitcnt lgkmcnt(2)
	v_mfma_f32_16x16x32_bf16 v[6:9], v[198:201], v[130:133], v[6:9]
	s_waitcnt lgkmcnt(0)
	v_mfma_f32_16x16x32_bf16 v[2:5], v[202:205], v[130:133], v[2:5]
	s_setprio 0
	s_add_i32 s44, s44, 64
	v_lshl_add_u64 v[150:151], v[150:151], 0, s[72:73]
	v_lshl_add_u64 v[152:153], v[152:153], 0, s[72:73]
	v_lshl_add_u64 v[154:155], v[154:155], 0, s[72:73]
	s_cmpk_lg_i32 s44, 0xc0
	v_lshl_add_u64 v[156:157], v[156:157], 0, s[72:73]
	s_cbranch_scc0 .LBB0_597
	s_mov_b32 s15, s14
	s_branch .LBB0_601
